# P4 DFT epilogue: ctx tiles (single full-K add onto zeroed yfn) use plain stores instead of float atomics
# speedup vs baseline: 1.0034x; 1.0034x over previous
.LBB0_452:
	s_cmpk_gt_i32 s17, 0x1ff
	s_cbranch_scc1 .Lp4_stv
	v_lshlrev_b32_e32 v2, 6, v113
	v_lshrrev_b32_e32 v3, 2, v110
	v_and_or_b32 v2, v3, 12, v2
	v_lshlrev_b32_e32 v1, 7, v1
	v_lshlrev_b32_e32 v3, 6, v111
	v_add_u32_e32 v0, v2, v0
	v_or3_b32 v100, v1, v3, v112
	v_ashrrev_i32_e32 v1, 31, v0
	v_add_u32_e32 v6, 1, v0
	v_lshlrev_b64 v[2:3], 10, v[0:1]
	v_ashrrev_i32_e32 v7, 31, v6
	v_add_u32_e32 v8, 2, v0
	v_lshl_add_u64 v[2:3], s[46:47], 0, v[2:3]
	v_lshlrev_b64 v[4:5], 2, v[100:101]
	v_lshlrev_b64 v[6:7], 10, v[6:7]
	v_ashrrev_i32_e32 v9, 31, v8
	v_add_u32_e32 v10, 3, v0
	v_lshl_add_u64 v[2:3], v[2:3], 0, v[4:5]
	v_mul_f32_e32 v1, s0, v92
	v_lshl_add_u64 v[6:7], s[46:47], 0, v[6:7]
	v_lshlrev_b64 v[8:9], 10, v[8:9]
	v_ashrrev_i32_e32 v11, 31, v10
	global_atomic_add_f32 v[2:3], v1, off
	v_lshl_add_u64 v[6:7], v[6:7], 0, v[4:5]
	v_mul_f32_e32 v1, s0, v93
	v_lshl_add_u64 v[8:9], s[46:47], 0, v[8:9]
	v_lshlrev_b64 v[10:11], 10, v[10:11]
	global_atomic_add_f32 v[6:7], v1, off
	v_lshl_add_u64 v[8:9], v[8:9], 0, v[4:5]
	v_mul_f32_e32 v1, s0, v94
	v_lshl_add_u64 v[10:11], s[46:47], 0, v[10:11]
	global_atomic_add_f32 v[8:9], v1, off
	v_lshl_add_u64 v[10:11], v[10:11], 0, v[4:5]
	v_mul_f32_e32 v1, s0, v95
	global_atomic_add_f32 v[10:11], v1, off
	v_mul_f32_e32 v1, s0, v88
	global_atomic_add_f32 v[2:3], v1, off offset:64
	v_mul_f32_e32 v1, s0, v89
	global_atomic_add_f32 v[6:7], v1, off offset:64
	v_mul_f32_e32 v1, s0, v90
	global_atomic_add_f32 v[8:9], v1, off offset:64
	v_mul_f32_e32 v1, s0, v91
	global_atomic_add_f32 v[10:11], v1, off offset:64
	v_mul_f32_e32 v1, s0, v84
	global_atomic_add_f32 v[2:3], v1, off offset:128
	v_mul_f32_e32 v1, s0, v85
	global_atomic_add_f32 v[6:7], v1, off offset:128
	v_mul_f32_e32 v1, s0, v86
	global_atomic_add_f32 v[8:9], v1, off offset:128
	v_mul_f32_e32 v1, s0, v87
	global_atomic_add_f32 v[10:11], v1, off offset:128
	v_mul_f32_e32 v1, s0, v80
	global_atomic_add_f32 v[2:3], v1, off offset:192
	v_mul_f32_e32 v1, s0, v81
	v_add_u32_e32 v2, 16, v0
	global_atomic_add_f32 v[6:7], v1, off offset:192
	v_mul_f32_e32 v1, s0, v82
	v_ashrrev_i32_e32 v3, 31, v2
	v_add_u32_e32 v6, 17, v0
	global_atomic_add_f32 v[8:9], v1, off offset:192
	v_mul_f32_e32 v1, s0, v83
	v_lshlrev_b64 v[2:3], 10, v[2:3]
	v_ashrrev_i32_e32 v7, 31, v6
	v_add_u32_e32 v8, 18, v0
	global_atomic_add_f32 v[10:11], v1, off offset:192
	v_lshl_add_u64 v[2:3], s[46:47], 0, v[2:3]
	v_lshlrev_b64 v[6:7], 10, v[6:7]
	v_ashrrev_i32_e32 v9, 31, v8
	v_add_u32_e32 v10, 19, v0
	v_lshl_add_u64 v[2:3], v[2:3], 0, v[4:5]
	v_mul_f32_e32 v1, s0, v76
	v_lshl_add_u64 v[6:7], s[46:47], 0, v[6:7]
	v_lshlrev_b64 v[8:9], 10, v[8:9]
	v_ashrrev_i32_e32 v11, 31, v10
	global_atomic_add_f32 v[2:3], v1, off
	v_lshl_add_u64 v[6:7], v[6:7], 0, v[4:5]
	v_mul_f32_e32 v1, s0, v77
	v_lshl_add_u64 v[8:9], s[46:47], 0, v[8:9]
	v_lshlrev_b64 v[10:11], 10, v[10:11]
	global_atomic_add_f32 v[6:7], v1, off
	v_lshl_add_u64 v[8:9], v[8:9], 0, v[4:5]
	v_mul_f32_e32 v1, s0, v78
	v_lshl_add_u64 v[10:11], s[46:47], 0, v[10:11]
	global_atomic_add_f32 v[8:9], v1, off
	v_lshl_add_u64 v[10:11], v[10:11], 0, v[4:5]
	v_mul_f32_e32 v1, s0, v79
	global_atomic_add_f32 v[10:11], v1, off
	v_mul_f32_e32 v1, s0, v72
	global_atomic_add_f32 v[2:3], v1, off offset:64
	v_mul_f32_e32 v1, s0, v73
	global_atomic_add_f32 v[6:7], v1, off offset:64
	v_mul_f32_e32 v1, s0, v74
	global_atomic_add_f32 v[8:9], v1, off offset:64
	v_mul_f32_e32 v1, s0, v75
	global_atomic_add_f32 v[10:11], v1, off offset:64
	v_mul_f32_e32 v1, s0, v68
	global_atomic_add_f32 v[2:3], v1, off offset:128
	v_mul_f32_e32 v1, s0, v69
	global_atomic_add_f32 v[6:7], v1, off offset:128
	v_mul_f32_e32 v1, s0, v70
	global_atomic_add_f32 v[8:9], v1, off offset:128
	v_mul_f32_e32 v1, s0, v71
	global_atomic_add_f32 v[10:11], v1, off offset:128
	v_mul_f32_e32 v1, s0, v64
	global_atomic_add_f32 v[2:3], v1, off offset:192
	v_mul_f32_e32 v1, s0, v65
	v_add_u32_e32 v2, 32, v0
	global_atomic_add_f32 v[6:7], v1, off offset:192
	v_mul_f32_e32 v1, s0, v66
	v_ashrrev_i32_e32 v3, 31, v2
	v_add_u32_e32 v6, 33, v0
	global_atomic_add_f32 v[8:9], v1, off offset:192
	v_mul_f32_e32 v1, s0, v67
	v_lshlrev_b64 v[2:3], 10, v[2:3]
	v_ashrrev_i32_e32 v7, 31, v6
	v_add_u32_e32 v8, 34, v0
	global_atomic_add_f32 v[10:11], v1, off offset:192
	v_lshl_add_u64 v[2:3], s[46:47], 0, v[2:3]
	v_lshlrev_b64 v[6:7], 10, v[6:7]
	v_ashrrev_i32_e32 v9, 31, v8
	v_add_u32_e32 v10, 35, v0
	v_lshl_add_u64 v[2:3], v[2:3], 0, v[4:5]
	v_mul_f32_e32 v1, s0, v56
	v_lshl_add_u64 v[6:7], s[46:47], 0, v[6:7]
	v_lshlrev_b64 v[8:9], 10, v[8:9]
	v_ashrrev_i32_e32 v11, 31, v10
	global_atomic_add_f32 v[2:3], v1, off
	v_lshl_add_u64 v[6:7], v[6:7], 0, v[4:5]
	v_mul_f32_e32 v1, s0, v57
	v_lshl_add_u64 v[8:9], s[46:47], 0, v[8:9]
	v_lshlrev_b64 v[10:11], 10, v[10:11]
	global_atomic_add_f32 v[6:7], v1, off
	v_lshl_add_u64 v[8:9], v[8:9], 0, v[4:5]
	v_mul_f32_e32 v1, s0, v58
	v_lshl_add_u64 v[10:11], s[46:47], 0, v[10:11]
	global_atomic_add_f32 v[8:9], v1, off
	v_lshl_add_u64 v[10:11], v[10:11], 0, v[4:5]
	v_mul_f32_e32 v1, s0, v59
	global_atomic_add_f32 v[10:11], v1, off
	v_mul_f32_e32 v1, s0, v40
	global_atomic_add_f32 v[2:3], v1, off offset:64
	v_mul_f32_e32 v1, s0, v41
	global_atomic_add_f32 v[6:7], v1, off offset:64
	v_mul_f32_e32 v1, s0, v42
	global_atomic_add_f32 v[8:9], v1, off offset:64
	v_mul_f32_e32 v1, s0, v43
	global_atomic_add_f32 v[10:11], v1, off offset:64
	v_mul_f32_e32 v1, s0, v36
	global_atomic_add_f32 v[2:3], v1, off offset:128
	v_mul_f32_e32 v1, s0, v37
	global_atomic_add_f32 v[6:7], v1, off offset:128
	v_mul_f32_e32 v1, s0, v38
	global_atomic_add_f32 v[8:9], v1, off offset:128
	v_mul_f32_e32 v1, s0, v39
	global_atomic_add_f32 v[10:11], v1, off offset:128
	v_mul_f32_e32 v1, s0, v32
	global_atomic_add_f32 v[2:3], v1, off offset:192
	v_mul_f32_e32 v1, s0, v33
	v_add_u32_e32 v2, 48, v0
	global_atomic_add_f32 v[6:7], v1, off offset:192
	v_mul_f32_e32 v1, s0, v34
	v_ashrrev_i32_e32 v3, 31, v2
	v_add_u32_e32 v6, 49, v0
	global_atomic_add_f32 v[8:9], v1, off offset:192
	v_lshlrev_b64 v[2:3], 10, v[2:3]
	v_ashrrev_i32_e32 v7, 31, v6
	v_add_u32_e32 v8, 50, v0
	v_mul_f32_e32 v1, s0, v35
	v_lshl_add_u64 v[2:3], s[46:47], 0, v[2:3]
	v_lshlrev_b64 v[6:7], 10, v[6:7]
	v_ashrrev_i32_e32 v9, 31, v8
	global_atomic_add_f32 v[10:11], v1, off offset:192
	v_lshl_add_u64 v[2:3], v[2:3], 0, v[4:5]
	v_mul_f32_e32 v1, s0, v44
	v_lshl_add_u64 v[6:7], s[46:47], 0, v[6:7]
	v_lshlrev_b64 v[8:9], 10, v[8:9]
	global_atomic_add_f32 v[2:3], v1, off
	v_lshl_add_u64 v[6:7], v[6:7], 0, v[4:5]
	v_mul_f32_e32 v1, s0, v45
	v_lshl_add_u64 v[8:9], s[46:47], 0, v[8:9]
	global_atomic_add_f32 v[6:7], v1, off
	v_lshl_add_u64 v[8:9], v[8:9], 0, v[4:5]
	v_mul_f32_e32 v1, s0, v46
	v_add_u32_e32 v0, 51, v0
	global_atomic_add_f32 v[8:9], v1, off
	v_ashrrev_i32_e32 v1, 31, v0
	v_lshlrev_b64 v[0:1], 10, v[0:1]
	v_lshl_add_u64 v[0:1], s[46:47], 0, v[0:1]
	v_lshl_add_u64 v[0:1], v[0:1], 0, v[4:5]
	v_mul_f32_e32 v4, s0, v47
	global_atomic_add_f32 v[0:1], v4, off
	v_mul_f32_e32 v4, s0, v48
	global_atomic_add_f32 v[2:3], v4, off offset:64
	v_mul_f32_e32 v4, s0, v49
	global_atomic_add_f32 v[6:7], v4, off offset:64
	v_mul_f32_e32 v4, s0, v50
	global_atomic_add_f32 v[8:9], v4, off offset:64
	v_mul_f32_e32 v4, s0, v51
	global_atomic_add_f32 v[0:1], v4, off offset:64
	v_mul_f32_e32 v4, s0, v52
	global_atomic_add_f32 v[2:3], v4, off offset:128
	v_mul_f32_e32 v4, s0, v53
	global_atomic_add_f32 v[6:7], v4, off offset:128
	v_mul_f32_e32 v4, s0, v54
	global_atomic_add_f32 v[8:9], v4, off offset:128
	v_mul_f32_e32 v4, s0, v55
	global_atomic_add_f32 v[0:1], v4, off offset:128
	v_mul_f32_e32 v4, s0, v60
	global_atomic_add_f32 v[2:3], v4, off offset:192
	v_mul_f32_e32 v2, s0, v61
	global_atomic_add_f32 v[6:7], v2, off offset:192
	v_mul_f32_e32 v2, s0, v62
	global_atomic_add_f32 v[8:9], v2, off offset:192
	v_mul_f32_e32 v2, s0, v63
	global_atomic_add_f32 v[0:1], v2, off offset:192
.Lp4_latch:
	s_add_i32 s17, s17, s92
	s_add_i32 s12, s12, s13
	s_add_i32 s14, s14, s15
	s_cmpk_gt_i32 s17, 0x23f
	s_cbranch_scc1 .LBB0_494
	s_branch .LBB0_453
.Lp4_stv:
	v_lshlrev_b32_e32 v2, 6, v113
	v_lshrrev_b32_e32 v3, 2, v110
	v_and_or_b32 v2, v3, 12, v2
	v_lshlrev_b32_e32 v1, 7, v1
	v_lshlrev_b32_e32 v3, 6, v111
	v_add_u32_e32 v0, v2, v0
	v_or3_b32 v100, v1, v3, v112
	v_ashrrev_i32_e32 v1, 31, v0
	v_add_u32_e32 v6, 1, v0
	v_lshlrev_b64 v[2:3], 10, v[0:1]
	v_ashrrev_i32_e32 v7, 31, v6
	v_add_u32_e32 v8, 2, v0
	v_lshl_add_u64 v[2:3], s[46:47], 0, v[2:3]
	v_lshlrev_b64 v[4:5], 2, v[100:101]
	v_lshlrev_b64 v[6:7], 10, v[6:7]
	v_ashrrev_i32_e32 v9, 31, v8
	v_add_u32_e32 v10, 3, v0
	v_lshl_add_u64 v[2:3], v[2:3], 0, v[4:5]
	v_mul_f32_e32 v1, s0, v92
	v_lshl_add_u64 v[6:7], s[46:47], 0, v[6:7]
	v_lshlrev_b64 v[8:9], 10, v[8:9]
	v_ashrrev_i32_e32 v11, 31, v10
	global_store_dword v[2:3], v1, off
	v_lshl_add_u64 v[6:7], v[6:7], 0, v[4:5]
	v_mul_f32_e32 v1, s0, v93
	v_lshl_add_u64 v[8:9], s[46:47], 0, v[8:9]
	v_lshlrev_b64 v[10:11], 10, v[10:11]
	global_store_dword v[6:7], v1, off
	v_lshl_add_u64 v[8:9], v[8:9], 0, v[4:5]
	v_mul_f32_e32 v1, s0, v94
	v_lshl_add_u64 v[10:11], s[46:47], 0, v[10:11]
	global_store_dword v[8:9], v1, off
	v_lshl_add_u64 v[10:11], v[10:11], 0, v[4:5]
	v_mul_f32_e32 v1, s0, v95
	global_store_dword v[10:11], v1, off
	v_mul_f32_e32 v1, s0, v88
	global_store_dword v[2:3], v1, off offset:64
	v_mul_f32_e32 v1, s0, v89
	global_store_dword v[6:7], v1, off offset:64
	v_mul_f32_e32 v1, s0, v90
	global_store_dword v[8:9], v1, off offset:64
	v_mul_f32_e32 v1, s0, v91
	global_store_dword v[10:11], v1, off offset:64
	v_mul_f32_e32 v1, s0, v84
	global_store_dword v[2:3], v1, off offset:128
	v_mul_f32_e32 v1, s0, v85
	global_store_dword v[6:7], v1, off offset:128
	v_mul_f32_e32 v1, s0, v86
	global_store_dword v[8:9], v1, off offset:128
	v_mul_f32_e32 v1, s0, v87
	global_store_dword v[10:11], v1, off offset:128
	v_mul_f32_e32 v1, s0, v80
	global_store_dword v[2:3], v1, off offset:192
	v_mul_f32_e32 v1, s0, v81
	v_add_u32_e32 v2, 16, v0
	global_store_dword v[6:7], v1, off offset:192
	v_mul_f32_e32 v1, s0, v82
	v_ashrrev_i32_e32 v3, 31, v2
	v_add_u32_e32 v6, 17, v0
	global_store_dword v[8:9], v1, off offset:192
	v_mul_f32_e32 v1, s0, v83
	v_lshlrev_b64 v[2:3], 10, v[2:3]
	v_ashrrev_i32_e32 v7, 31, v6
	v_add_u32_e32 v8, 18, v0
	global_store_dword v[10:11], v1, off offset:192
	v_lshl_add_u64 v[2:3], s[46:47], 0, v[2:3]
	v_lshlrev_b64 v[6:7], 10, v[6:7]
	v_ashrrev_i32_e32 v9, 31, v8
	v_add_u32_e32 v10, 19, v0
	v_lshl_add_u64 v[2:3], v[2:3], 0, v[4:5]
	v_mul_f32_e32 v1, s0, v76
	v_lshl_add_u64 v[6:7], s[46:47], 0, v[6:7]
	v_lshlrev_b64 v[8:9], 10, v[8:9]
	v_ashrrev_i32_e32 v11, 31, v10
	global_store_dword v[2:3], v1, off
	v_lshl_add_u64 v[6:7], v[6:7], 0, v[4:5]
	v_mul_f32_e32 v1, s0, v77
	v_lshl_add_u64 v[8:9], s[46:47], 0, v[8:9]
	v_lshlrev_b64 v[10:11], 10, v[10:11]
	global_store_dword v[6:7], v1, off
	v_lshl_add_u64 v[8:9], v[8:9], 0, v[4:5]
	v_mul_f32_e32 v1, s0, v78
	v_lshl_add_u64 v[10:11], s[46:47], 0, v[10:11]
	global_store_dword v[8:9], v1, off
	v_lshl_add_u64 v[10:11], v[10:11], 0, v[4:5]
	v_mul_f32_e32 v1, s0, v79
	global_store_dword v[10:11], v1, off
	v_mul_f32_e32 v1, s0, v72
	global_store_dword v[2:3], v1, off offset:64
	v_mul_f32_e32 v1, s0, v73
	global_store_dword v[6:7], v1, off offset:64
	v_mul_f32_e32 v1, s0, v74
	global_store_dword v[8:9], v1, off offset:64
	v_mul_f32_e32 v1, s0, v75
	global_store_dword v[10:11], v1, off offset:64
	v_mul_f32_e32 v1, s0, v68
	global_store_dword v[2:3], v1, off offset:128
	v_mul_f32_e32 v1, s0, v69
	global_store_dword v[6:7], v1, off offset:128
	v_mul_f32_e32 v1, s0, v70
	global_store_dword v[8:9], v1, off offset:128
	v_mul_f32_e32 v1, s0, v71
	global_store_dword v[10:11], v1, off offset:128
	v_mul_f32_e32 v1, s0, v64
	global_store_dword v[2:3], v1, off offset:192
	v_mul_f32_e32 v1, s0, v65
	v_add_u32_e32 v2, 32, v0
	global_store_dword v[6:7], v1, off offset:192
	v_mul_f32_e32 v1, s0, v66
	v_ashrrev_i32_e32 v3, 31, v2
	v_add_u32_e32 v6, 33, v0
	global_store_dword v[8:9], v1, off offset:192
	v_mul_f32_e32 v1, s0, v67
	v_lshlrev_b64 v[2:3], 10, v[2:3]
	v_ashrrev_i32_e32 v7, 31, v6
	v_add_u32_e32 v8, 34, v0
	global_store_dword v[10:11], v1, off offset:192
	v_lshl_add_u64 v[2:3], s[46:47], 0, v[2:3]
	v_lshlrev_b64 v[6:7], 10, v[6:7]
	v_ashrrev_i32_e32 v9, 31, v8
	v_add_u32_e32 v10, 35, v0
	v_lshl_add_u64 v[2:3], v[2:3], 0, v[4:5]
	v_mul_f32_e32 v1, s0, v56
	v_lshl_add_u64 v[6:7], s[46:47], 0, v[6:7]
	v_lshlrev_b64 v[8:9], 10, v[8:9]
	v_ashrrev_i32_e32 v11, 31, v10
	global_store_dword v[2:3], v1, off
	v_lshl_add_u64 v[6:7], v[6:7], 0, v[4:5]
	v_mul_f32_e32 v1, s0, v57
	v_lshl_add_u64 v[8:9], s[46:47], 0, v[8:9]
	v_lshlrev_b64 v[10:11], 10, v[10:11]
	global_store_dword v[6:7], v1, off
	v_lshl_add_u64 v[8:9], v[8:9], 0, v[4:5]
	v_mul_f32_e32 v1, s0, v58
	v_lshl_add_u64 v[10:11], s[46:47], 0, v[10:11]
	global_store_dword v[8:9], v1, off
	v_lshl_add_u64 v[10:11], v[10:11], 0, v[4:5]
	v_mul_f32_e32 v1, s0, v59
	global_store_dword v[10:11], v1, off
	v_mul_f32_e32 v1, s0, v40
	global_store_dword v[2:3], v1, off offset:64
	v_mul_f32_e32 v1, s0, v41
	global_store_dword v[6:7], v1, off offset:64
	v_mul_f32_e32 v1, s0, v42
	global_store_dword v[8:9], v1, off offset:64
	v_mul_f32_e32 v1, s0, v43
	global_store_dword v[10:11], v1, off offset:64
	v_mul_f32_e32 v1, s0, v36
	global_store_dword v[2:3], v1, off offset:128
	v_mul_f32_e32 v1, s0, v37
	global_store_dword v[6:7], v1, off offset:128
	v_mul_f32_e32 v1, s0, v38
	global_store_dword v[8:9], v1, off offset:128
	v_mul_f32_e32 v1, s0, v39
	global_store_dword v[10:11], v1, off offset:128
	v_mul_f32_e32 v1, s0, v32
	global_store_dword v[2:3], v1, off offset:192
	v_mul_f32_e32 v1, s0, v33
	v_add_u32_e32 v2, 48, v0
	global_store_dword v[6:7], v1, off offset:192
	v_mul_f32_e32 v1, s0, v34
	v_ashrrev_i32_e32 v3, 31, v2
	v_add_u32_e32 v6, 49, v0
	global_store_dword v[8:9], v1, off offset:192
	v_lshlrev_b64 v[2:3], 10, v[2:3]
	v_ashrrev_i32_e32 v7, 31, v6
	v_add_u32_e32 v8, 50, v0
	v_mul_f32_e32 v1, s0, v35
	v_lshl_add_u64 v[2:3], s[46:47], 0, v[2:3]
	v_lshlrev_b64 v[6:7], 10, v[6:7]
	v_ashrrev_i32_e32 v9, 31, v8
	global_store_dword v[10:11], v1, off offset:192
	v_lshl_add_u64 v[2:3], v[2:3], 0, v[4:5]
	v_mul_f32_e32 v1, s0, v44
	v_lshl_add_u64 v[6:7], s[46:47], 0, v[6:7]
	v_lshlrev_b64 v[8:9], 10, v[8:9]
	global_store_dword v[2:3], v1, off
	v_lshl_add_u64 v[6:7], v[6:7], 0, v[4:5]
	v_mul_f32_e32 v1, s0, v45
	v_lshl_add_u64 v[8:9], s[46:47], 0, v[8:9]
	global_store_dword v[6:7], v1, off
	v_lshl_add_u64 v[8:9], v[8:9], 0, v[4:5]
	v_mul_f32_e32 v1, s0, v46
	v_add_u32_e32 v0, 51, v0
	global_store_dword v[8:9], v1, off
	v_ashrrev_i32_e32 v1, 31, v0
	v_lshlrev_b64 v[0:1], 10, v[0:1]
	v_lshl_add_u64 v[0:1], s[46:47], 0, v[0:1]
	v_lshl_add_u64 v[0:1], v[0:1], 0, v[4:5]
	v_mul_f32_e32 v4, s0, v47
	global_store_dword v[0:1], v4, off
	v_mul_f32_e32 v4, s0, v48
	global_store_dword v[2:3], v4, off offset:64
	v_mul_f32_e32 v4, s0, v49
	global_store_dword v[6:7], v4, off offset:64
	v_mul_f32_e32 v4, s0, v50
	global_store_dword v[8:9], v4, off offset:64
	v_mul_f32_e32 v4, s0, v51
	global_store_dword v[0:1], v4, off offset:64
	v_mul_f32_e32 v4, s0, v52
	global_store_dword v[2:3], v4, off offset:128
	v_mul_f32_e32 v4, s0, v53
	global_store_dword v[6:7], v4, off offset:128
	v_mul_f32_e32 v4, s0, v54
	global_store_dword v[8:9], v4, off offset:128
	v_mul_f32_e32 v4, s0, v55
	global_store_dword v[0:1], v4, off offset:128
	v_mul_f32_e32 v4, s0, v60
	global_store_dword v[2:3], v4, off offset:192
	v_mul_f32_e32 v2, s0, v61
	global_store_dword v[6:7], v2, off offset:192
	v_mul_f32_e32 v2, s0, v62
	global_store_dword v[8:9], v2, off offset:192
	v_mul_f32_e32 v2, s0, v63
	global_store_dword v[0:1], v2, off offset:192
	s_branch .Lp4_latch
